# RG-LRU final pass output: 9 serialized silu(gate)*h blocks batched (all LDS reads first, arithmetic interleaved across elements)
# speedup vs baseline: 1.1017x; 1.0037x over previous
; template <bool FINAL>
; __device__ void phase_lru(const Params& p, int l, unsigned char* smem) {
;     ...
;         float h = d ? cin1 : cin0;
;         if (d == 0) {
; #pragma unroll
;           for (int q = 0; q < 4; ++q) if (q < qd) h = part[q * 64 + e_] * h + part[(4 + q) * 64 + e_];
; #pragma unroll
;           for (int tt = 0; tt < 16; ++tt) { int t = qd * 16 + tt; h = sa[t * 64 + e_] * h + sb[t * 64 + e_]; hsum[tt] += h; }
;         } else {
; #pragma unroll
;           for (int q = 3; q >= 0; --q) if (q > qd) h = part[q * 64 + e_] * h + part[(4 + q) * 64 + e_];
; #pragma unroll
;     ...
;         }
.LBB0_198:
	s_or_b64 exec, exec, s[56:57]
	v_fmac_f32_e32 v95, v162, v94
	v_fmac_f32_e32 v93, v95, v92
	v_fmac_f32_e32 v91, v93, v90
	v_fmac_f32_e32 v89, v91, v88
	ds_read2st64_b32 v[12:13], v132 offset0:134 offset1:198
	v_fmac_f32_e32 v87, v89, v86
	ds_read2st64_b32 v[14:15], v131 offset0:134 offset1:198
	v_fmac_f32_e32 v85, v87, v84
	ds_read2st64_b32 v[16:17], v130 offset0:134 offset1:198
	v_fmac_f32_e32 v83, v85, v82
	ds_read2st64_b32 v[18:19], v129 offset0:134 offset1:198
	v_fmac_f32_e32 v81, v83, v80
	ds_read2st64_b32 v[20:21], v128 offset0:134 offset1:198
	v_fmac_f32_e32 v79, v81, v78
	s_waitcnt lgkmcnt(4)
	v_fmac_f32_e32 v13, v161, v12
	ds_read2st64_b32 v[22:23], v127 offset0:134 offset1:198
	v_fmac_f32_e32 v77, v79, v76
	s_waitcnt lgkmcnt(4)
	v_fmac_f32_e32 v15, v13, v14
	ds_read2st64_b32 v[24:25], v126 offset0:134 offset1:198
	v_fmac_f32_e32 v75, v77, v74
	s_waitcnt lgkmcnt(4)
	v_fmac_f32_e32 v17, v15, v16
	ds_read2st64_b32 v[26:27], v125 offset0:134 offset1:198
	v_fmac_f32_e32 v73, v75, v72
	s_waitcnt lgkmcnt(4)
	v_fmac_f32_e32 v19, v17, v18
	ds_read2st64_b32 v[28:29], v124 offset0:134 offset1:198
	v_fmac_f32_e32 v71, v73, v70
	s_waitcnt lgkmcnt(4)
	v_fmac_f32_e32 v21, v19, v20
	v_fmac_f32_e32 v69, v71, v68
	s_waitcnt lgkmcnt(3)
	v_fmac_f32_e32 v23, v21, v22
	v_fmac_f32_e32 v65, v69, v64
	s_waitcnt lgkmcnt(2)
	v_fmac_f32_e32 v25, v23, v24
	v_fmac_f32_e32 v67, v65, v66
	s_waitcnt lgkmcnt(1)
	v_fmac_f32_e32 v27, v25, v26
	v_add_f32_e32 v74, 0, v75
	v_add_f32_e32 v72, 0, v73
	v_add_f32_e32 v70, 0, v71
	v_add_f32_e32 v71, 0, v69
	v_add_f32_e32 v73, 0, v65
	v_add_f32_e32 v75, 0, v67
	s_waitcnt lgkmcnt(0)
	v_fmac_f32_e32 v29, v27, v28
	ds_read2st64_b32 v[30:31], v123 offset0:134 offset1:198
	ds_read2st64_b32 v[32:33], v122 offset0:134 offset1:198
	ds_read2st64_b32 v[34:35], v121 offset0:134 offset1:198
	ds_read2st64_b32 v[62:63], v120 offset0:134 offset1:198
	ds_read2st64_b32 v[64:65], v119 offset0:134 offset1:198
	ds_read2st64_b32 v[66:67], v118 offset0:134 offset1:198
	ds_read2st64_b32 v[68:69], v59 offset0:134 offset1:198
	s_waitcnt lgkmcnt(0)
	s_barrier
; __device__ __forceinline__ float bf2f(unsigned h) { return __uint_as_float(h << 16); }
; __device__ __forceinline__ float siluf_(float x) { return x * __builtin_amdgcn_rcpf(1.0f + __expf(-x)); }
; template <bool FINAL>
; __device__ void phase_lru(const Params& p, int l, unsigned char* smem) {
;     ...
;         }
;       }
;       __syncthreads();
;     }
;     if (FINAL) {
; #pragma unroll
;       for (int tt = 0; tt < 16; ++tt) {
;         const int t = qd * 16 + tt;
;         const float gzv = bf2f(xs[t * 64 + e_]);
;         ub[t * 72 + e_] = (u16)f2bf(hsum[tt] * siluf_(gzv));
;       }
;       __syncthreads();
;       u16* ob = p.ACT + (size_t)tb * DM + 256 + nb * 64 + (tid & 7) * 8;
;       *(uint4*)(ob + (size_t)(tid >> 3) * DM) = *(const uint4*)(ub + (tid >> 3) * 72 + (tid & 7) * 8);
;       *(uint4*)(ob + (size_t)((tid >> 3) + 32) * DM) = *(const uint4*)(ub + ((tid >> 3) + 32) * 72 + (tid & 7) * 8);
	ds_read_u16 v28, v158
	v_add_f32_e32 v80, 0, v81
	v_fmac_f32_e32 v31, v29, v30
	v_add_f32_e32 v26, v80, v29
	v_fmac_f32_e32 v33, v31, v32
	s_waitcnt lgkmcnt(0)
	v_lshlrev_b32_e32 v28, 16, v28
	v_mul_f32_e32 v29, 0xbfb8aa3b, v28
	v_exp_f32_e32 v29, v29
	v_fmac_f32_e32 v35, v33, v34
	v_fmac_f32_e32 v63, v35, v62
	v_fmac_f32_e32 v65, v63, v64
	v_add_f32_e32 v29, 1.0, v29
	v_rcp_f32_e32 v29, v29
	v_fmac_f32_e32 v67, v65, v66
	v_add_f32_e32 v61, 0, v95
	v_fmac_f32_e32 v69, v67, v68
	v_add_f32_e32 v12, v61, v69
	v_mul_f32_e32 v28, v29, v28
	v_mul_f32_e32 v12, v12, v28
	v_cvt_pk_bf16_f32 v12, v12, s0
	ds_write_b16 v159, v12 offset:25088
	ds_read_u16 v12, v138
	v_add_f32_e32 v92, 0, v93
	v_add_f32_e32 v14, v92, v67
	v_add_f32_e32 v90, 0, v91
	v_add_f32_e32 v16, v90, v65
	s_waitcnt lgkmcnt(0)
	v_lshlrev_b32_e32 v12, 16, v12
	v_mul_f32_e32 v28, 0xbfb8aa3b, v12
	v_exp_f32_e32 v28, v28
	v_add_f32_e32 v88, 0, v89
	v_add_f32_e32 v18, v88, v63
	v_add_f32_e32 v86, 0, v87
	v_add_f32_e32 v28, 1.0, v28
	v_rcp_f32_e32 v28, v28
	v_add_f32_e32 v20, v86, v35
	v_add_f32_e32 v84, 0, v85
	v_add_f32_e32 v22, v84, v33
	v_mul_f32_e32 v12, v28, v12
	v_mul_f32_e32 v12, v14, v12
	v_cvt_pk_bf16_f32 v12, v12, s0
	ds_write_b16 v160, v12 offset:25088
	ds_read_u16 v12, v139
	v_add_f32_e32 v82, 0, v83
	v_add_f32_e32 v24, v82, v31
	v_add_f32_e32 v78, 0, v79
	v_add_f32_e32 v27, v78, v27
	s_waitcnt lgkmcnt(0)
	v_lshlrev_b32_e32 v12, 16, v12
	v_mul_f32_e32 v14, 0xbfb8aa3b, v12
	v_exp_f32_e32 v14, v14
	v_add_f32_e32 v76, 0, v77
	v_add_f32_e32 v25, v76, v25
	v_add_f32_e32 v23, v74, v23
	v_add_f32_e32 v14, 1.0, v14
	v_rcp_f32_e32 v14, v14
	v_add_f32_e32 v21, v72, v21
	v_add_f32_e32 v19, v70, v19
	v_add_f32_e32 v17, v71, v17
	v_mul_f32_e32 v12, v14, v12
	v_mul_f32_e32 v12, v16, v12
	v_cvt_pk_bf16_f32 v12, v12, s0
	ds_write_b16 v160, v12 offset:25232
	ds_read_u16 v12, v140
	v_add_f32_e32 v15, v73, v15
	v_add_f32_e32 v13, v75, v13
	s_lshl_b64 s[40:41], s[92:93], 11
	s_add_u32 s40, s80, s40
	s_waitcnt lgkmcnt(0)
	v_lshlrev_b32_e32 v12, 16, v12
	v_mul_f32_e32 v14, 0xbfb8aa3b, v12
	v_exp_f32_e32 v14, v14
	s_addc_u32 s41, s81, s41
	s_add_u32 s40, s40, s98
	s_addc_u32 s41, s41, 0
	v_add_f32_e32 v14, 1.0, v14
	v_rcp_f32_e32 v14, v14
	v_mov_b32_e32 v61, v145
	v_readlane_b32 s4, v248, 28
	s_add_i32 s99, s99, s4
	v_mul_f32_e32 v12, v14, v12
	v_mul_f32_e32 v12, v18, v12
	v_cvt_pk_bf16_f32 v12, v12, s0
	ds_write_b16 v160, v12 offset:25376
	ds_read_u16 v12, v141
	v_readlane_b32 s4, v249, 63
	s_add_i32 s97, s97, s4
	s_andn2_b64 vcc, exec, s[74:75]
	v_readlane_b32 s5, v248, 29
	s_waitcnt lgkmcnt(0)
	v_lshlrev_b32_e32 v12, 16, v12
	v_mul_f32_e32 v14, 0xbfb8aa3b, v12
	v_exp_f32_e32 v14, v14
	s_nop 0
	v_add_f32_e32 v14, 1.0, v14
	v_rcp_f32_e32 v14, v14
	s_nop 0
	v_mul_f32_e32 v12, v14, v12
	v_mul_f32_e32 v12, v20, v12
	v_cvt_pk_bf16_f32 v12, v12, s0
	ds_write_b16 v160, v12 offset:25520
	ds_read_u16 v62, v142
	ds_read_u16 v63, v143
	ds_read_u16 v64, v149
	ds_read_u16 v65, v150
	ds_read_u16 v66, v151
	ds_read_u16 v67, v152
	ds_read_u16 v68, v153
	ds_read_u16 v69, v154
	ds_read_u16 v70, v155
	s_waitcnt lgkmcnt(0)
	v_lshlrev_b32_e32 v62, 16, v62
	v_lshlrev_b32_e32 v63, 16, v63
	v_lshlrev_b32_e32 v64, 16, v64
	v_lshlrev_b32_e32 v65, 16, v65
	v_lshlrev_b32_e32 v66, 16, v66
	v_lshlrev_b32_e32 v67, 16, v67
	v_lshlrev_b32_e32 v68, 16, v68
	v_lshlrev_b32_e32 v69, 16, v69
	v_lshlrev_b32_e32 v70, 16, v70
	v_mul_f32_e32 v71, 0xbfb8aa3b, v62
	v_mul_f32_e32 v72, 0xbfb8aa3b, v63
	v_mul_f32_e32 v73, 0xbfb8aa3b, v64
	v_mul_f32_e32 v74, 0xbfb8aa3b, v65
	v_mul_f32_e32 v75, 0xbfb8aa3b, v66
	v_mul_f32_e32 v76, 0xbfb8aa3b, v67
	v_mul_f32_e32 v77, 0xbfb8aa3b, v68
	v_mul_f32_e32 v78, 0xbfb8aa3b, v69
	v_mul_f32_e32 v79, 0xbfb8aa3b, v70
	v_exp_f32_e32 v71, v71
	v_exp_f32_e32 v72, v72
	v_exp_f32_e32 v73, v73
	v_exp_f32_e32 v74, v74
	v_exp_f32_e32 v75, v75
	v_exp_f32_e32 v76, v76
	v_exp_f32_e32 v77, v77
	v_exp_f32_e32 v78, v78
	v_exp_f32_e32 v79, v79
	v_add_f32_e32 v71, 1.0, v71
	v_add_f32_e32 v72, 1.0, v72
	v_add_f32_e32 v73, 1.0, v73
	v_add_f32_e32 v74, 1.0, v74
	v_add_f32_e32 v75, 1.0, v75
	v_add_f32_e32 v76, 1.0, v76
	v_add_f32_e32 v77, 1.0, v77
	v_add_f32_e32 v78, 1.0, v78
	v_add_f32_e32 v79, 1.0, v79
	v_rcp_f32_e32 v71, v71
	v_rcp_f32_e32 v72, v72
	v_rcp_f32_e32 v73, v73
	v_rcp_f32_e32 v74, v74
	v_rcp_f32_e32 v75, v75
	v_rcp_f32_e32 v76, v76
	v_rcp_f32_e32 v77, v77
	v_rcp_f32_e32 v78, v78
	v_rcp_f32_e32 v79, v79
	v_mul_f32_e32 v62, v71, v62
	v_mul_f32_e32 v63, v72, v63
	v_mul_f32_e32 v64, v73, v64
	v_mul_f32_e32 v65, v74, v65
	v_mul_f32_e32 v66, v75, v66
	v_mul_f32_e32 v67, v76, v67
	v_mul_f32_e32 v68, v77, v68
	v_mul_f32_e32 v69, v78, v69
	v_mul_f32_e32 v70, v79, v70
	v_mul_f32_e32 v62, v22, v62
	v_mul_f32_e32 v63, v24, v63
	v_mul_f32_e32 v64, v26, v64
	v_mul_f32_e32 v65, v27, v65
	v_mul_f32_e32 v66, v25, v66
	v_mul_f32_e32 v67, v23, v67
	v_mul_f32_e32 v68, v21, v68
	v_mul_f32_e32 v69, v19, v69
	v_mul_f32_e32 v70, v17, v70
	v_cvt_pk_bf16_f32 v62, v62, s0
	v_cvt_pk_bf16_f32 v63, v63, s0
	v_cvt_pk_bf16_f32 v64, v64, s0
	v_cvt_pk_bf16_f32 v65, v65, s0
	v_cvt_pk_bf16_f32 v66, v66, s0
	v_cvt_pk_bf16_f32 v67, v67, s0
	v_cvt_pk_bf16_f32 v68, v68, s0
	v_cvt_pk_bf16_f32 v69, v69, s0
	v_cvt_pk_bf16_f32 v70, v70, s0
	ds_write_b16 v160, v62 offset:25664
	ds_write_b16 v160, v63 offset:25808
	ds_write_b16 v160, v64 offset:25952
	ds_write_b16 v160, v65 offset:26096
	ds_write_b16 v160, v66 offset:26240
	ds_write_b16 v160, v67 offset:26384
	ds_write_b16 v160, v68 offset:26528
	ds_write_b16 v160, v69 offset:26672
	ds_write_b16 v160, v70 offset:26816
	ds_read_u16 v12, v156
	v_lshl_add_u64 v[16:17], s[40:41], 0, v[60:61]
	v_lshl_add_u64 v[18:19], v[16:17], 0, v[54:55]
	v_lshl_add_u64 v[16:17], v[16:17], 0, v[56:57]
	s_waitcnt lgkmcnt(0)
	v_lshlrev_b32_e32 v12, 16, v12
	v_mul_f32_e32 v14, 0xbfb8aa3b, v12
	v_exp_f32_e32 v14, v14
	s_nop 0
	v_add_f32_e32 v14, 1.0, v14
	v_rcp_f32_e32 v14, v14
	s_nop 0
	v_mul_f32_e32 v12, v14, v12
	v_mul_f32_e32 v12, v15, v12
	v_cvt_pk_bf16_f32 v12, v12, s0
	ds_write_b16 v160, v12 offset:26960
	ds_read_u16 v12, v157
	s_waitcnt lgkmcnt(0)
	v_lshlrev_b32_e32 v12, 16, v12
	v_mul_f32_e32 v14, 0xbfb8aa3b, v12
	v_exp_f32_e32 v14, v14
	s_nop 0
	v_add_f32_e32 v14, 1.0, v14
	v_rcp_f32_e32 v14, v14
	s_nop 0
	v_mul_f32_e32 v12, v14, v12
	v_mul_f32_e32 v12, v13, v12
	v_cvt_pk_bf16_f32 v12, v12, s0
	ds_write_b16 v160, v12 offset:27104
	s_waitcnt lgkmcnt(0)
	s_barrier
	ds_read_b128 v[12:15], v101
	s_waitcnt lgkmcnt(0)
	global_store_dwordx4 v[18:19], v[12:15], off offset:512
	ds_read_b128 v[12:15], v37
	s_waitcnt lgkmcnt(0)
	global_store_dwordx4 v[16:17], v[12:15], off offset:512
	s_cbranch_vccz .LBB0_225
